# P1 K-prep hook: hand-written fast path for the partial-rotary k tiles (only the 16 rotated dims per head are read/rotated/written, all loads issued up front); generic hook: DPP zero-inits dropped, bf1
# speedup vs baseline: 1.0061x; 1.0061x over previous
; #define ARG_WS() ((unsigned char*)karg<128>())
;     __device__ __forceinline__ void done(const pg8::Unit& u) const {
;         const int colt = u.pn * 256;
;         if (even ? !(colt == 512 || colt == 1280 || colt == 1536) : (colt != 1024)) return;
;         asm volatile("s_waitcnt vmcnt(0)" ::: "memory");
;         __builtin_amdgcn_s_barrier();
;         asm volatile("" ::: "memory");
;         int tid_ = threadIdx.x; asm volatile("" : "+v"(tid_));
;         const int sub = tid_ & 7, gidx = tid_ >> 3;
;         unsigned char* const ws = ARG_WS(); bf16* const QKV = (bf16*)(ws + WS_QKV); const f32x2* const ropeT = (const f32x2*)(ws + WS_ROPE); const f32x2* const axT = (const f32x2*)(ws + WS_AX);
;         const float* const qkg = ARG_IN(4) + (size_t)l2 * 128;
;         const int PITCH = nN * 256;
;         const int nh = (even && colt == 512) ? 2 : 4;
;         const int nit = (256 * nh) / 64;
;         constexpr int U = 4;
; #pragma unroll 1
;         for (int it = 0; it < nit; it += U) {
;             bf16* p[U]; int type[U]; v4u raw[U]; f32x4 tb[U][4];
; #pragma unroll
;             for (int k = 0; k < U; ++k) {
;                 const int hvi = (it + k) * 64 + gidx, rl = (nh == 2) ? (hvi >> 1) : (hvi >> 2), col = colt + 64 * ((nh == 2) ? (hvi & 1) : (hvi & 3)), row = u.pm * 256 + rl;
;                 const int ty = (even && colt == 512) ? 1 : 3;
;                 type[k] = ty; p[k] = QKV + (size_t)row * PITCH + col + 8 * sub;
;                 raw[k] = *(const v4u*)p[k];
;                 const int t = row < MP ? (row & 8191) : (row & 4095);
;                 const int aidx = (sub < 4) ? (t >> 6) : (t & 63);
;                 const f32x2* cs = (ty < 2) ? axT + aidx * 16 + 8 * (sub & 1) : ropeT + t * 8;
;                 tb[k][0] = *(const f32x4*)(cs); tb[k][1] = *(const f32x4*)(cs + 2); tb[k][2] = *(const f32x4*)(cs + 4); tb[k][3] = *(const f32x4*)(cs + 6);
.LBB0_133:
	s_and_b64 vcc, exec, s[8:9]
	s_cbranch_vccz .LBB0_221
	v_readlane_b32 s2, v255, 9
	v_mov_b32_e32 v6, v240
	v_readlane_b32 s3, v255, 10
	s_waitcnt vmcnt(0)
	s_barrier
	s_load_dwordx2 s[92:93], s[2:3], 0x80
	s_waitcnt lgkmcnt(0)
	s_load_dwordx2 s[2:3], s[2:3], 32
	s_waitcnt lgkmcnt(0)
	s_add_u32 s10, s2, s33
	s_addc_u32 s11, s3, 0
	s_cmp_eq_u32 s6, 2
	s_cselect_b64 s[2:3], -1, 0
	s_and_b64 s[6:7], s[74:75], s[2:3]
	s_xor_b64 s[94:95], s[6:7], -1
	s_and_b64 s[2:3], s[6:7], exec
	v_ashrrev_i32_e32 v103, 3, v6
	s_cselect_b32 s8, 1, 3
	v_and_b32_e32 v2, s8, v103
	v_and_b32_e32 v102, 7, v6
	v_lshl_or_b32 v2, v2, 6, s15
	v_mov_b32_e32 v3, v0
	v_lshl_add_u64 v[2:3], v[2:3], 1, s[92:93]
	v_lshlrev_b32_e32 v4, 4, v102
	v_mov_b32_e32 v5, v0
	v_lshl_add_u64 v[2:3], v[2:3], 0, v[4:5]
	s_mov_b64 s[8:9], 0x19a00000
	v_lshl_add_u64 v[82:83], v[2:3], 0, s[8:9]
	v_lshlrev_b32_e32 v2, 6, v6
	v_and_b32_e32 v2, 64, v2
	v_mov_b32_e32 v3, v0
	v_lshl_add_u64 v[2:3], s[92:93], 0, v[2:3]
	s_mov_b64 s[20:21], 0x80000
	v_lshl_add_u64 v[84:85], v[2:3], 0, s[20:21]
	v_lshlrev_b32_e32 v2, 5, v102
	v_mov_b32_e32 v3, v0
	s_cselect_b32 s2, 8, 16
	s_cselect_b32 s3, 1, 2
	v_cmp_gt_u32_e64 s[8:9], 4, v102
	v_lshl_add_u64 v[86:87], s[10:11], 0, v[2:3]
	v_cmp_gt_u32_e64 s[96:97], 2, v102
	s_cmp_eq_u64 s[6:7], 0
	s_cbranch_scc1 .Lmy_k3
	s_mov_b32 s15, 0
	s_branch .LBB0_137

; __device__ __forceinline__ unsigned pk2(float lo, float hi) { return f2bf(lo) | (f2bf(hi) << 16); }
; template <int CTRL> __device__ __forceinline__ float dppf(float v) { return __builtin_bit_cast(float, __builtin_amdgcn_update_dpp(0, __builtin_bit_cast(int, v), CTRL, 0xf, 0xf, false)); }
; __device__ __forceinline__ v4u prep_compute(const v4u rw, const f32x4 (&tb)[4], int type, int sub, const float* qkg) {
;     ...
;     const bool active = isA || sub < 2;
;     const float sg = (isA ? (sub & 2) : (sub & 1)) ? 1.f : -1.f;
; #pragma unroll
;     for (int i = 0; i < 8; ++i) {
;         const float p1 = dppf<DPP_XOR1>(v[i]), p2 = dppf<DPP_XOR2>(v[i]);
;         const float pr = isA ? p2 : p1;
;         const float rv = v[i] * cc[i] + sg * (pr * sn[i]);
;         v[i] = active ? rv : v[i];
;     }
;     v4u o; o.x = pk2(v[0], v[1]); o.y = pk2(v[2], v[3]); o.z = pk2(v[4], v[5]); o.w = pk2(v[6], v[7]);
.LBB0_136:
	v_and_b32_e32 v20, s20, v102
	v_cmp_eq_u32_e32 vcc, 0, v20
	v_mov_b32_dpp v20, v26 quad_perm:[1,0,3,2] row_mask:0xf bank_mask:0xf
	v_mov_b32_dpp v21, v26 quad_perm:[2,3,0,1] row_mask:0xf bank_mask:0xf
	v_cndmask_b32_e64 v20, v20, v21, s[6:7]
	v_mov_b32_dpp v28, v24 quad_perm:[2,3,0,1] row_mask:0xf bank_mask:0xf
	v_mov_b32_dpp v21, v24 quad_perm:[1,0,3,2] row_mask:0xf bank_mask:0xf
	v_cndmask_b32_e64 v28, v21, v28, s[6:7]
	v_mov_b32_dpp v29, v27 quad_perm:[2,3,0,1] row_mask:0xf bank_mask:0xf
	v_mov_b32_dpp v21, v27 quad_perm:[1,0,3,2] row_mask:0xf bank_mask:0xf
	v_cndmask_b32_e64 v21, v21, v29, s[6:7]
	v_mov_b32_dpp v30, v25 quad_perm:[2,3,0,1] row_mask:0xf bank_mask:0xf
	v_mov_b32_dpp v29, v25 quad_perm:[1,0,3,2] row_mask:0xf bank_mask:0xf
	v_cndmask_b32_e64 v29, v29, v30, s[6:7]
	v_mov_b32_dpp v31, v22 quad_perm:[2,3,0,1] row_mask:0xf bank_mask:0xf
	v_mov_b32_dpp v30, v22 quad_perm:[1,0,3,2] row_mask:0xf bank_mask:0xf
	v_cndmask_b32_e64 v30, v30, v31, s[6:7]
	v_mov_b32_dpp v32, v18 quad_perm:[2,3,0,1] row_mask:0xf bank_mask:0xf
	v_mov_b32_dpp v31, v18 quad_perm:[1,0,3,2] row_mask:0xf bank_mask:0xf
	v_cndmask_b32_e64 v32, v31, v32, s[6:7]
	v_mov_b32_dpp v33, v23 quad_perm:[2,3,0,1] row_mask:0xf bank_mask:0xf
	v_mov_b32_dpp v31, v23 quad_perm:[1,0,3,2] row_mask:0xf bank_mask:0xf
	v_cndmask_b32_e64 v31, v31, v33, s[6:7]
	s_waitcnt vmcnt(4)
	v_mov_b32_e32 v35, v10
	s_waitcnt vmcnt(3)
	v_mov_b32_e32 v10, v15
	v_mov_b32_dpp v33, v19 quad_perm:[1,0,3,2] row_mask:0xf bank_mask:0xf
	v_mov_b32_dpp v34, v19 quad_perm:[2,3,0,1] row_mask:0xf bank_mask:0xf
	v_pk_mul_f32 v[10:11], v[10:11], v[20:21]
	v_cndmask_b32_e64 v33, v33, v34, s[6:7]
	v_mov_b32_e32 v34, v14
	v_cndmask_b32_e64 v11, v11, -v11, vcc
	v_cndmask_b32_e64 v10, v10, -v10, vcc
	v_pk_fma_f32 v[10:11], v[34:35], v[26:27], v[10:11]
	s_add_i32 s15, s15, 4
	v_cndmask_b32_e64 v14, v27, v11, s[10:11]
	v_mov_b32_e32 v11, v12
	v_mov_b32_e32 v12, v17
	v_pk_mul_f32 v[12:13], v[12:13], v[28:29]
	v_cndmask_b32_e64 v15, v26, v10, s[10:11]
	v_mov_b32_e32 v10, v16
	v_cndmask_b32_e64 v13, v13, -v13, vcc
	v_cndmask_b32_e64 v12, v12, -v12, vcc
	v_pk_fma_f32 v[10:11], v[10:11], v[24:25], v[12:13]
	v_add_u32_e32 v103, 0x100, v103
	v_cndmask_b32_e64 v13, v25, v11, s[10:11]
	v_mov_b32_e32 v11, v2
	v_mov_b32_e32 v2, v7
	v_pk_mul_f32 v[2:3], v[2:3], v[30:31]
	v_cndmask_b32_e64 v12, v24, v10, s[10:11]
	v_mov_b32_e32 v10, v6
	v_cndmask_b32_e64 v3, v3, -v3, vcc
	v_cndmask_b32_e64 v2, v2, -v2, vcc
	v_pk_fma_f32 v[2:3], v[10:11], v[22:23], v[2:3]
	s_cmp_ge_u32 s15, s2
	v_cndmask_b32_e64 v6, v23, v3, s[10:11]
	v_mov_b32_e32 v3, v4
	v_mov_b32_e32 v4, v9
	v_pk_mul_f32 v[4:5], v[4:5], v[32:33]
	v_cndmask_b32_e64 v7, v22, v2, s[10:11]
	v_mov_b32_e32 v2, v8
	v_cndmask_b32_e64 v5, v5, -v5, vcc
	v_cndmask_b32_e64 v4, v4, -v4, vcc
	v_pk_fma_f32 v[2:3], v[2:3], v[18:19], v[4:5]
	v_cndmask_b32_e64 v2, v18, v2, s[10:11]
	v_cndmask_b32_e64 v3, v19, v3, s[10:11]
	v_cvt_pk_bf16_f32 v5, v6, v3
	v_cvt_pk_bf16_f32 v4, v7, v2
	v_cvt_pk_bf16_f32 v3, v14, v13
	v_cvt_pk_bf16_f32 v2, v15, v12
	global_store_dwordx4 v[88:89], v[2:5], off
	s_cbranch_scc1 .LBB0_220

; __device__ __forceinline__ unsigned pk2(float lo, float hi) { return f2bf(lo) | (f2bf(hi) << 16); }
; template <int CTRL> __device__ __forceinline__ float dppf(float v) { return __builtin_bit_cast(float, __builtin_amdgcn_update_dpp(0, __builtin_bit_cast(int, v), CTRL, 0xf, 0xf, false)); }
; __device__ __forceinline__ float sum8(float v) { v += dppf<DPP_XOR1>(v); v += dppf<DPP_XOR2>(v); v += dppf<DPP_HMIR>(v); return v; }
; __device__ __forceinline__ v4u prep_compute(const v4u rw, const f32x4 (&tb)[4], int type, int sub, const float* qkg) {
;     ...
;     float v[8] = {bflo(rw.x), bfhi(rw.x), bflo(rw.y), bfhi(rw.y), bflo(rw.z), bfhi(rw.z), bflo(rw.w), bfhi(rw.w)};
;     float ss = 0.f;
; #pragma unroll
;     for (int i = 0; i < 8; ++i) ss += v[i] * v[i];
;     ss = sum8(ss);
;     const float rn = isA ? __builtin_amdgcn_rsqf(ss * (1.f / 64.f) + EPSN) : 1.f;
;     const float* gp = qkg + (type & 1) * 64 + 8 * sub;
; #pragma unroll
;     for (int i = 0; i < 8; ++i) v[i] = isA ? (v[i] * rn) * gp[i] : v[i];
;     const bool active = isA || sub < 2;
;     const float sg = (isA ? (sub & 2) : (sub & 1)) ? 1.f : -1.f;
; #pragma unroll
;     for (int i = 0; i < 8; ++i) {
;         const float p1 = dppf<DPP_XOR1>(v[i]), p2 = dppf<DPP_XOR2>(v[i]);
;         const float pr = isA ? p2 : p1;
;         const float rv = v[i] * cc[i] + sg * (pr * sn[i]);
;         v[i] = active ? rv : v[i];
;     }
;     v4u o; o.x = pk2(v[0], v[1]); o.y = pk2(v[2], v[3]); o.z = pk2(v[4], v[5]); o.w = pk2(v[6], v[7]);
.LBB0_170:
	v_and_b32_e32 v80, s20, v102
	v_cmp_eq_u32_e32 vcc, 0, v80
	v_mov_b32_dpp v80, v100 quad_perm:[1,0,3,2] row_mask:0xf bank_mask:0xf
	v_mov_b32_dpp v81, v100 quad_perm:[2,3,0,1] row_mask:0xf bank_mask:0xf
	v_cndmask_b32_e64 v80, v80, v81, s[6:7]
	v_mov_b32_dpp v104, v98 quad_perm:[2,3,0,1] row_mask:0xf bank_mask:0xf
	v_mov_b32_dpp v81, v98 quad_perm:[1,0,3,2] row_mask:0xf bank_mask:0xf
	v_cndmask_b32_e64 v104, v81, v104, s[6:7]
	v_mov_b32_dpp v105, v101 quad_perm:[2,3,0,1] row_mask:0xf bank_mask:0xf
	v_mov_b32_dpp v81, v101 quad_perm:[1,0,3,2] row_mask:0xf bank_mask:0xf
	v_cndmask_b32_e64 v81, v81, v105, s[6:7]
	v_mov_b32_dpp v106, v99 quad_perm:[2,3,0,1] row_mask:0xf bank_mask:0xf
	v_mov_b32_dpp v105, v99 quad_perm:[1,0,3,2] row_mask:0xf bank_mask:0xf
	v_cndmask_b32_e64 v105, v105, v106, s[6:7]
	v_mov_b32_dpp v107, v96 quad_perm:[2,3,0,1] row_mask:0xf bank_mask:0xf
	v_mov_b32_dpp v106, v96 quad_perm:[1,0,3,2] row_mask:0xf bank_mask:0xf
	v_cndmask_b32_e64 v106, v106, v107, s[6:7]
	v_mov_b32_dpp v108, v78 quad_perm:[2,3,0,1] row_mask:0xf bank_mask:0xf
	v_mov_b32_dpp v107, v78 quad_perm:[1,0,3,2] row_mask:0xf bank_mask:0xf
	v_cndmask_b32_e64 v108, v107, v108, s[6:7]
	v_mov_b32_dpp v109, v97 quad_perm:[2,3,0,1] row_mask:0xf bank_mask:0xf
	v_mov_b32_dpp v107, v97 quad_perm:[1,0,3,2] row_mask:0xf bank_mask:0xf
	v_cndmask_b32_e64 v107, v107, v109, s[6:7]
	s_waitcnt vmcnt(16)
	v_mov_b32_e32 v111, v70
	s_waitcnt vmcnt(15)
	v_mov_b32_e32 v70, v75
	v_mov_b32_dpp v109, v79 quad_perm:[1,0,3,2] row_mask:0xf bank_mask:0xf
	v_mov_b32_dpp v110, v79 quad_perm:[2,3,0,1] row_mask:0xf bank_mask:0xf
	v_pk_mul_f32 v[70:71], v[70:71], v[80:81]
	v_cndmask_b32_e64 v109, v109, v110, s[6:7]
	v_mov_b32_e32 v110, v74
	v_cndmask_b32_e64 v71, v71, -v71, vcc
	v_cndmask_b32_e64 v70, v70, -v70, vcc
	v_pk_fma_f32 v[70:71], v[110:111], v[100:101], v[70:71]
	s_nop 0
	v_cndmask_b32_e64 v74, v101, v71, s[36:37]
	v_mov_b32_e32 v71, v72
	v_mov_b32_e32 v72, v77
	v_pk_mul_f32 v[72:73], v[72:73], v[104:105]
	v_cndmask_b32_e64 v75, v100, v70, s[36:37]
	v_mov_b32_e32 v70, v76
	v_cndmask_b32_e64 v73, v73, -v73, vcc
	v_cndmask_b32_e64 v72, v72, -v72, vcc
	v_pk_fma_f32 v[70:71], v[70:71], v[98:99], v[72:73]
	s_nop 0
	v_cndmask_b32_e64 v73, v99, v71, s[36:37]
	v_mov_b32_e32 v71, v62
	v_mov_b32_e32 v62, v67
	v_pk_mul_f32 v[62:63], v[62:63], v[106:107]
	v_cndmask_b32_e64 v72, v98, v70, s[36:37]
	v_mov_b32_e32 v70, v66
	v_cndmask_b32_e64 v63, v63, -v63, vcc
	v_cndmask_b32_e64 v62, v62, -v62, vcc
	v_pk_fma_f32 v[62:63], v[70:71], v[96:97], v[62:63]
	s_nop 0
	v_cndmask_b32_e64 v66, v97, v63, s[36:37]
	v_mov_b32_e32 v63, v64
	v_mov_b32_e32 v64, v69
	v_pk_mul_f32 v[64:65], v[64:65], v[108:109]
	v_cndmask_b32_e64 v67, v96, v62, s[36:37]
	v_mov_b32_e32 v62, v68
	v_cndmask_b32_e64 v65, v65, -v65, vcc
	v_cndmask_b32_e64 v64, v64, -v64, vcc
	v_pk_fma_f32 v[62:63], v[62:63], v[78:79], v[64:65]
	v_cndmask_b32_e64 v62, v78, v62, s[36:37]
	v_cndmask_b32_e64 v63, v79, v63, s[36:37]
	v_cvt_pk_bf16_f32 v65, v66, v63
	v_cvt_pk_bf16_f32 v64, v67, v62
	v_cvt_pk_bf16_f32 v63, v74, v73
	v_cvt_pk_bf16_f32 v62, v75, v72
	global_store_dwordx4 v[94:95], v[62:65], off
	s_waitcnt vmcnt(15)
	v_lshlrev_b32_e32 v66, 16, v58
	v_lshlrev_b32_e32 v67, 16, v59
	v_and_b32_e32 v64, 0xffff0000, v58
	v_lshlrev_b32_e32 v62, 16, v60
	v_and_b32_e32 v58, 0xffff0000, v60
	v_mul_f32_e32 v60, v64, v64
	v_fmac_f32_e32 v60, v66, v66
	v_and_b32_e32 v65, 0xffff0000, v59
	v_fmac_f32_e32 v60, v67, v67
	v_fmac_f32_e32 v60, v65, v65
	v_fmac_f32_e32 v60, v62, v62
	v_lshlrev_b32_e32 v63, 16, v61
	v_fmac_f32_e32 v60, v58, v58
	v_and_b32_e32 v59, 0xffff0000, v61
	v_fmac_f32_e32 v60, v63, v63
	v_fmac_f32_e32 v60, v59, v59
	s_and_b64 vcc, exec, s[10:11]
	s_nop 0
	v_add_f32_dpp v60, v60, v60 quad_perm:[1,0,3,2] row_mask:0xf bank_mask:0xf bound_ctrl:1
	s_nop 1
	v_add_f32_dpp v60, v60, v60 quad_perm:[2,3,0,1] row_mask:0xf bank_mask:0xf bound_ctrl:1
	s_nop 1
	v_add_f32_dpp v60, v60, v60 row_half_mirror row_mask:0xf bank_mask:0xf bound_ctrl:1
	v_fmamk_f32 v60, v60, 0x3c800000, v241
	v_rsq_f32_e32 v60, v60
	s_cbranch_vccz .LBB0_179
	s_and_b64 vcc, exec, s[10:11]
	s_cbranch_vccz .LBB0_180

; __device__ __forceinline__ unsigned pk2(float lo, float hi) { return f2bf(lo) | (f2bf(hi) << 16); }
; template <int CTRL> __device__ __forceinline__ float dppf(float v) { return __builtin_bit_cast(float, __builtin_amdgcn_update_dpp(0, __builtin_bit_cast(int, v), CTRL, 0xf, 0xf, false)); }
; __device__ __forceinline__ float sum8(float v) { v += dppf<DPP_XOR1>(v); v += dppf<DPP_XOR2>(v); v += dppf<DPP_HMIR>(v); return v; }
; __device__ __forceinline__ v4u prep_compute(const v4u rw, const f32x4 (&tb)[4], int type, int sub, const float* qkg) {
;     ...
;     float v[8] = {bflo(rw.x), bfhi(rw.x), bflo(rw.y), bfhi(rw.y), bflo(rw.z), bfhi(rw.z), bflo(rw.w), bfhi(rw.w)};
;     float ss = 0.f;
; #pragma unroll
;     for (int i = 0; i < 8; ++i) ss += v[i] * v[i];
;     ss = sum8(ss);
;     const float rn = isA ? __builtin_amdgcn_rsqf(ss * (1.f / 64.f) + EPSN) : 1.f;
;     const float* gp = qkg + (type & 1) * 64 + 8 * sub;
; #pragma unroll
;     for (int i = 0; i < 8; ++i) v[i] = isA ? (v[i] * rn) * gp[i] : v[i];
;     const bool active = isA || sub < 2;
;     const float sg = (isA ? (sub & 2) : (sub & 1)) ? 1.f : -1.f;
; #pragma unroll
;     for (int i = 0; i < 8; ++i) {
;         const float p1 = dppf<DPP_XOR1>(v[i]), p2 = dppf<DPP_XOR2>(v[i]);
;         const float pr = isA ? p2 : p1;
;         const float rv = v[i] * cc[i] + sg * (pr * sn[i]);
;         v[i] = active ? rv : v[i];
;     }
;     v4u o; o.x = pk2(v[0], v[1]); o.y = pk2(v[2], v[3]); o.z = pk2(v[4], v[5]); o.w = pk2(v[6], v[7]);
.LBB0_187:
	v_and_b32_e32 v60, s20, v102
	v_cmp_eq_u32_e32 vcc, 0, v60
	v_mov_b32_dpp v60, v66 quad_perm:[1,0,3,2] row_mask:0xf bank_mask:0xf
	v_mov_b32_dpp v61, v66 quad_perm:[2,3,0,1] row_mask:0xf bank_mask:0xf
	v_cndmask_b32_e64 v60, v60, v61, s[6:7]
	v_mov_b32_dpp v68, v64 quad_perm:[2,3,0,1] row_mask:0xf bank_mask:0xf
	v_mov_b32_dpp v61, v64 quad_perm:[1,0,3,2] row_mask:0xf bank_mask:0xf
	v_cndmask_b32_e64 v68, v61, v68, s[6:7]
	v_mov_b32_dpp v69, v67 quad_perm:[2,3,0,1] row_mask:0xf bank_mask:0xf
	v_mov_b32_dpp v61, v67 quad_perm:[1,0,3,2] row_mask:0xf bank_mask:0xf
	v_cndmask_b32_e64 v61, v61, v69, s[6:7]
	v_mov_b32_dpp v70, v65 quad_perm:[2,3,0,1] row_mask:0xf bank_mask:0xf
	v_mov_b32_dpp v69, v65 quad_perm:[1,0,3,2] row_mask:0xf bank_mask:0xf
	v_cndmask_b32_e64 v69, v69, v70, s[6:7]
	v_mov_b32_dpp v71, v62 quad_perm:[2,3,0,1] row_mask:0xf bank_mask:0xf
	v_mov_b32_dpp v70, v62 quad_perm:[1,0,3,2] row_mask:0xf bank_mask:0xf
	v_cndmask_b32_e64 v70, v70, v71, s[6:7]
	v_mov_b32_dpp v72, v58 quad_perm:[2,3,0,1] row_mask:0xf bank_mask:0xf
	v_mov_b32_dpp v71, v58 quad_perm:[1,0,3,2] row_mask:0xf bank_mask:0xf
	v_cndmask_b32_e64 v72, v71, v72, s[6:7]
	v_mov_b32_dpp v73, v63 quad_perm:[2,3,0,1] row_mask:0xf bank_mask:0xf
	v_mov_b32_dpp v71, v63 quad_perm:[1,0,3,2] row_mask:0xf bank_mask:0xf
	v_cndmask_b32_e64 v71, v71, v73, s[6:7]
	s_waitcnt vmcnt(12)
	v_mov_b32_e32 v75, v50
	s_waitcnt vmcnt(11)
	v_mov_b32_e32 v50, v55
	v_mov_b32_dpp v73, v59 quad_perm:[1,0,3,2] row_mask:0xf bank_mask:0xf
	v_mov_b32_dpp v74, v59 quad_perm:[2,3,0,1] row_mask:0xf bank_mask:0xf
	v_pk_mul_f32 v[50:51], v[50:51], v[60:61]
	v_cndmask_b32_e64 v73, v73, v74, s[6:7]
	v_mov_b32_e32 v74, v54
	v_cndmask_b32_e64 v51, v51, -v51, vcc
	v_cndmask_b32_e64 v50, v50, -v50, vcc
	v_pk_fma_f32 v[50:51], v[74:75], v[66:67], v[50:51]
	s_nop 0
	v_cndmask_b32_e64 v54, v67, v51, s[36:37]
	v_mov_b32_e32 v51, v52
	v_mov_b32_e32 v52, v57
	v_pk_mul_f32 v[52:53], v[52:53], v[68:69]
	v_cndmask_b32_e64 v55, v66, v50, s[36:37]
	v_mov_b32_e32 v50, v56
	v_cndmask_b32_e64 v53, v53, -v53, vcc
	v_cndmask_b32_e64 v52, v52, -v52, vcc
	v_pk_fma_f32 v[50:51], v[50:51], v[64:65], v[52:53]
	s_nop 0
	v_cndmask_b32_e64 v53, v65, v51, s[36:37]
	v_mov_b32_e32 v51, v42
	v_mov_b32_e32 v42, v47
	v_pk_mul_f32 v[42:43], v[42:43], v[70:71]
	v_cndmask_b32_e64 v52, v64, v50, s[36:37]
	v_mov_b32_e32 v50, v46
	v_cndmask_b32_e64 v43, v43, -v43, vcc
	v_cndmask_b32_e64 v42, v42, -v42, vcc
	v_pk_fma_f32 v[42:43], v[50:51], v[62:63], v[42:43]
	s_nop 0
	v_cndmask_b32_e64 v46, v63, v43, s[36:37]
	v_mov_b32_e32 v43, v44
	v_mov_b32_e32 v44, v49
	v_pk_mul_f32 v[44:45], v[44:45], v[72:73]
	v_cndmask_b32_e64 v47, v62, v42, s[36:37]
	v_mov_b32_e32 v42, v48
	v_cndmask_b32_e64 v45, v45, -v45, vcc
	v_cndmask_b32_e64 v44, v44, -v44, vcc
	v_pk_fma_f32 v[42:43], v[42:43], v[58:59], v[44:45]
	v_cndmask_b32_e64 v42, v58, v42, s[36:37]
	v_cndmask_b32_e64 v43, v59, v43, s[36:37]
	v_cvt_pk_bf16_f32 v45, v46, v43
	v_cvt_pk_bf16_f32 v44, v47, v42
	v_cvt_pk_bf16_f32 v43, v54, v53
	v_cvt_pk_bf16_f32 v42, v55, v52
	global_store_dwordx4 v[92:93], v[42:45], off
	s_waitcnt vmcnt(11)
	v_lshlrev_b32_e32 v46, 16, v38
	v_lshlrev_b32_e32 v47, 16, v39
	v_and_b32_e32 v44, 0xffff0000, v38
	v_lshlrev_b32_e32 v42, 16, v40
	v_and_b32_e32 v38, 0xffff0000, v40
	v_mul_f32_e32 v40, v44, v44
	v_fmac_f32_e32 v40, v46, v46
	v_and_b32_e32 v45, 0xffff0000, v39
	v_fmac_f32_e32 v40, v47, v47
	v_fmac_f32_e32 v40, v45, v45
	v_fmac_f32_e32 v40, v42, v42
	v_lshlrev_b32_e32 v43, 16, v41
	v_fmac_f32_e32 v40, v38, v38
	v_and_b32_e32 v39, 0xffff0000, v41
	v_fmac_f32_e32 v40, v43, v43
	v_fmac_f32_e32 v40, v39, v39
	s_and_b64 vcc, exec, s[10:11]
	s_nop 0
	v_add_f32_dpp v40, v40, v40 quad_perm:[1,0,3,2] row_mask:0xf bank_mask:0xf bound_ctrl:1
	s_nop 1
	v_add_f32_dpp v40, v40, v40 quad_perm:[2,3,0,1] row_mask:0xf bank_mask:0xf bound_ctrl:1
	s_nop 1
	v_add_f32_dpp v40, v40, v40 row_half_mirror row_mask:0xf bank_mask:0xf bound_ctrl:1
	v_fmamk_f32 v40, v40, 0x3c800000, v241
	v_rsq_f32_e32 v40, v40
	s_cbranch_vccz .LBB0_196
	s_and_b64 vcc, exec, s[10:11]
	s_cbranch_vccz .LBB0_197

; __device__ __forceinline__ unsigned pk2(float lo, float hi) { return f2bf(lo) | (f2bf(hi) << 16); }
; template <int CTRL> __device__ __forceinline__ float dppf(float v) { return __builtin_bit_cast(float, __builtin_amdgcn_update_dpp(0, __builtin_bit_cast(int, v), CTRL, 0xf, 0xf, false)); }
; __device__ __forceinline__ float sum8(float v) { v += dppf<DPP_XOR1>(v); v += dppf<DPP_XOR2>(v); v += dppf<DPP_HMIR>(v); return v; }
; __device__ __forceinline__ v4u prep_compute(const v4u rw, const f32x4 (&tb)[4], int type, int sub, const float* qkg) {
;     ...
;     float v[8] = {bflo(rw.x), bfhi(rw.x), bflo(rw.y), bfhi(rw.y), bflo(rw.z), bfhi(rw.z), bflo(rw.w), bfhi(rw.w)};
;     float ss = 0.f;
; #pragma unroll
;     for (int i = 0; i < 8; ++i) ss += v[i] * v[i];
;     ss = sum8(ss);
;     const float rn = isA ? __builtin_amdgcn_rsqf(ss * (1.f / 64.f) + EPSN) : 1.f;
;     const float* gp = qkg + (type & 1) * 64 + 8 * sub;
; #pragma unroll
;     for (int i = 0; i < 8; ++i) v[i] = isA ? (v[i] * rn) * gp[i] : v[i];
;     const bool active = isA || sub < 2;
;     const float sg = (isA ? (sub & 2) : (sub & 1)) ? 1.f : -1.f;
; #pragma unroll
;     for (int i = 0; i < 8; ++i) {
;         const float p1 = dppf<DPP_XOR1>(v[i]), p2 = dppf<DPP_XOR2>(v[i]);
;         const float pr = isA ? p2 : p1;
;         const float rv = v[i] * cc[i] + sg * (pr * sn[i]);
;         v[i] = active ? rv : v[i];
;     }
;     v4u o; o.x = pk2(v[0], v[1]); o.y = pk2(v[2], v[3]); o.z = pk2(v[4], v[5]); o.w = pk2(v[6], v[7]);
.LBB0_204:
	v_and_b32_e32 v40, s20, v102
	v_cmp_eq_u32_e32 vcc, 0, v40
	v_mov_b32_dpp v40, v46 quad_perm:[1,0,3,2] row_mask:0xf bank_mask:0xf
	v_mov_b32_dpp v41, v46 quad_perm:[2,3,0,1] row_mask:0xf bank_mask:0xf
	v_cndmask_b32_e64 v40, v40, v41, s[6:7]
	v_mov_b32_dpp v48, v44 quad_perm:[2,3,0,1] row_mask:0xf bank_mask:0xf
	v_mov_b32_dpp v41, v44 quad_perm:[1,0,3,2] row_mask:0xf bank_mask:0xf
	v_cndmask_b32_e64 v48, v41, v48, s[6:7]
	v_mov_b32_dpp v49, v47 quad_perm:[2,3,0,1] row_mask:0xf bank_mask:0xf
	v_mov_b32_dpp v41, v47 quad_perm:[1,0,3,2] row_mask:0xf bank_mask:0xf
	v_cndmask_b32_e64 v41, v41, v49, s[6:7]
	v_mov_b32_dpp v50, v45 quad_perm:[2,3,0,1] row_mask:0xf bank_mask:0xf
	v_mov_b32_dpp v49, v45 quad_perm:[1,0,3,2] row_mask:0xf bank_mask:0xf
	v_cndmask_b32_e64 v49, v49, v50, s[6:7]
	v_mov_b32_dpp v51, v42 quad_perm:[2,3,0,1] row_mask:0xf bank_mask:0xf
	v_mov_b32_dpp v50, v42 quad_perm:[1,0,3,2] row_mask:0xf bank_mask:0xf
	v_cndmask_b32_e64 v50, v50, v51, s[6:7]
	v_mov_b32_dpp v52, v38 quad_perm:[2,3,0,1] row_mask:0xf bank_mask:0xf
	v_mov_b32_dpp v51, v38 quad_perm:[1,0,3,2] row_mask:0xf bank_mask:0xf
	v_cndmask_b32_e64 v52, v51, v52, s[6:7]
	v_mov_b32_dpp v53, v43 quad_perm:[2,3,0,1] row_mask:0xf bank_mask:0xf
	v_mov_b32_dpp v51, v43 quad_perm:[1,0,3,2] row_mask:0xf bank_mask:0xf
	v_cndmask_b32_e64 v51, v51, v53, s[6:7]
	s_waitcnt vmcnt(8)
	v_mov_b32_e32 v55, v30
	s_waitcnt vmcnt(7)
	v_mov_b32_e32 v30, v35
	v_mov_b32_dpp v53, v39 quad_perm:[1,0,3,2] row_mask:0xf bank_mask:0xf
	v_mov_b32_dpp v54, v39 quad_perm:[2,3,0,1] row_mask:0xf bank_mask:0xf
	v_pk_mul_f32 v[30:31], v[30:31], v[40:41]
	v_cndmask_b32_e64 v53, v53, v54, s[6:7]
	v_mov_b32_e32 v54, v34
	v_cndmask_b32_e64 v31, v31, -v31, vcc
	v_cndmask_b32_e64 v30, v30, -v30, vcc
	v_pk_fma_f32 v[30:31], v[54:55], v[46:47], v[30:31]
	s_nop 0
	v_cndmask_b32_e64 v34, v47, v31, s[36:37]
	v_mov_b32_e32 v31, v32
	v_mov_b32_e32 v32, v37
	v_pk_mul_f32 v[32:33], v[32:33], v[48:49]
	v_cndmask_b32_e64 v35, v46, v30, s[36:37]
	v_mov_b32_e32 v30, v36
	v_cndmask_b32_e64 v33, v33, -v33, vcc
	v_cndmask_b32_e64 v32, v32, -v32, vcc
	v_pk_fma_f32 v[30:31], v[30:31], v[44:45], v[32:33]
	s_nop 0
	v_cndmask_b32_e64 v33, v45, v31, s[36:37]
	v_mov_b32_e32 v31, v22
	v_mov_b32_e32 v22, v27
	v_pk_mul_f32 v[22:23], v[22:23], v[50:51]
	v_cndmask_b32_e64 v32, v44, v30, s[36:37]
	v_mov_b32_e32 v30, v26
	v_cndmask_b32_e64 v23, v23, -v23, vcc
	v_cndmask_b32_e64 v22, v22, -v22, vcc
	v_pk_fma_f32 v[22:23], v[30:31], v[42:43], v[22:23]
	s_nop 0
	v_cndmask_b32_e64 v26, v43, v23, s[36:37]
	v_mov_b32_e32 v23, v24
	v_mov_b32_e32 v24, v29
	v_pk_mul_f32 v[24:25], v[24:25], v[52:53]
	v_cndmask_b32_e64 v27, v42, v22, s[36:37]
	v_mov_b32_e32 v22, v28
	v_cndmask_b32_e64 v25, v25, -v25, vcc
	v_cndmask_b32_e64 v24, v24, -v24, vcc
	v_pk_fma_f32 v[22:23], v[22:23], v[38:39], v[24:25]
	v_cndmask_b32_e64 v22, v38, v22, s[36:37]
	v_cndmask_b32_e64 v23, v39, v23, s[36:37]
	v_cvt_pk_bf16_f32 v25, v26, v23
	v_cvt_pk_bf16_f32 v24, v27, v22
	v_cvt_pk_bf16_f32 v23, v34, v33
	v_cvt_pk_bf16_f32 v22, v35, v32
	global_store_dwordx4 v[90:91], v[22:25], off
	s_waitcnt vmcnt(7)
	v_lshlrev_b32_e32 v26, 16, v18
	v_lshlrev_b32_e32 v27, 16, v19
	v_and_b32_e32 v24, 0xffff0000, v18
	v_lshlrev_b32_e32 v22, 16, v20
	v_and_b32_e32 v18, 0xffff0000, v20
	v_mul_f32_e32 v20, v24, v24
	v_fmac_f32_e32 v20, v26, v26
	v_and_b32_e32 v25, 0xffff0000, v19
	v_fmac_f32_e32 v20, v27, v27
	v_fmac_f32_e32 v20, v25, v25
	v_fmac_f32_e32 v20, v22, v22
	v_lshlrev_b32_e32 v23, 16, v21
	v_fmac_f32_e32 v20, v18, v18
	v_and_b32_e32 v19, 0xffff0000, v21
	v_fmac_f32_e32 v20, v23, v23
	v_fmac_f32_e32 v20, v19, v19
	s_and_b64 vcc, exec, s[10:11]
	s_nop 0
	v_add_f32_dpp v20, v20, v20 quad_perm:[1,0,3,2] row_mask:0xf bank_mask:0xf bound_ctrl:1
	s_nop 1
	v_add_f32_dpp v20, v20, v20 quad_perm:[2,3,0,1] row_mask:0xf bank_mask:0xf bound_ctrl:1
	s_nop 1
	v_add_f32_dpp v20, v20, v20 row_half_mirror row_mask:0xf bank_mask:0xf bound_ctrl:1
	v_fmamk_f32 v20, v20, 0x3c800000, v241
	v_rsq_f32_e32 v20, v20
	s_cbranch_vccz .LBB0_212
	s_and_b64 vcc, exec, s[10:11]
	s_cbranch_vccz .LBB0_213

; __device__ __forceinline__ unsigned pk2(float lo, float hi) { return f2bf(lo) | (f2bf(hi) << 16); }
; template <int CTRL> __device__ __forceinline__ float dppf(float v) { return __builtin_bit_cast(float, __builtin_amdgcn_update_dpp(0, __builtin_bit_cast(int, v), CTRL, 0xf, 0xf, false)); }
; __device__ __forceinline__ v4u prep_compute(const v4u rw, const f32x4 (&tb)[4], int type, int sub, const float* qkg) {
;     ...
;     const bool active = isA || sub < 2;
;     const float sg = (isA ? (sub & 2) : (sub & 1)) ? 1.f : -1.f;
; #pragma unroll
;     for (int i = 0; i < 8; ++i) {
;         const float p1 = dppf<DPP_XOR1>(v[i]), p2 = dppf<DPP_XOR2>(v[i]);
;         const float pr = isA ? p2 : p1;
;         const float rv = v[i] * cc[i] + sg * (pr * sn[i]);
;         v[i] = active ? rv : v[i];
;     }
;     v4u o; o.x = pk2(v[0], v[1]); o.y = pk2(v[2], v[3]); o.z = pk2(v[4], v[5]); o.w = pk2(v[6], v[7]);
;     __device__ __forceinline__ void done(const pg8::Unit& u) const {
;     ...
; #pragma unroll 1
;         for (int it = 0; it < nit; it += U) {
;             bf16* p[U]; int type[U]; v4u raw[U]; f32x4 tb[U][4];
; #pragma unroll
;             for (int k = 0; k < U; ++k) {
;                 const int hvi = (it + k) * 64 + gidx, rl = (nh == 2) ? (hvi >> 1) : (hvi >> 2), col = colt + 64 * ((nh == 2) ? (hvi & 1) : (hvi & 3)), row = u.pm * 256 + rl;
;                 const int ty = (even && colt == 512) ? 1 : 3;
;                 type[k] = ty; p[k] = QKV + (size_t)row * PITCH + col + 8 * sub;
;                 raw[k] = *(const v4u*)p[k];
;                 const int t = row < MP ? (row & 8191) : (row & 4095);
;                 const int aidx = (sub < 4) ? (t >> 6) : (t & 63);
;                 const f32x2* cs = (ty < 2) ? axT + aidx * 16 + 8 * (sub & 1) : ropeT + t * 8;
;                 tb[k][0] = *(const f32x4*)(cs); tb[k][1] = *(const f32x4*)(cs + 2); tb[k][2] = *(const f32x4*)(cs + 4); tb[k][3] = *(const f32x4*)(cs + 6);
;             }
; #pragma unroll
;             for (int k = 0; k < U; ++k) *(v4u*)p[k] = prep_compute(raw[k], tb[k], type[k], sub, qkg);
.Lmy_k3:
	v_and_b32_e32 v2, 1, v240
	v_bfe_u32 v3, v240, 1, 2
	v_lshrrev_b32_e32 v84, 3, v240
	v_add_u32_e32 v85, s46, v84
	v_mul_lo_u32 v86, v85, s0
	v_lshl_add_u32 v86, v3, 6, v86
	v_lshl_add_u32 v86, v2, 3, v86
	v_add_u32_e32 v86, s15, v86
	v_lshlrev_b32_e32 v86, 1, v86
	s_mul_i32 s2, s0, 0x80
	v_add_u32_e32 v87, s2, v86
	v_add_u32_e32 v88, s2, v87
	v_add_u32_e32 v89, s2, v88
	s_add_u32 s8, s92, 0x19a00000
	s_addc_u32 s9, s93, 0
	s_movk_i32 s3, 0xfff
	s_cmp_lt_u32 s46, s30
	s_cselect_b32 s3, 0x1fff, s3
	s_and_b32 s3, s46, s3
	v_add_u32_e32 v90, s3, v84
	v_lshlrev_b32_e32 v90, 6, v90
	v_add_u32_e32 v91, 0x1000, v90
	v_add_u32_e32 v92, 0x2000, v90
	v_add_u32_e32 v93, 0x3000, v90
	v_xor_b32_e32 v94, 1, v2
	v_lshlrev_b32_e32 v94, 31, v94
	global_load_dwordx4 v[4:7], v86, s[8:9]
	global_load_dwordx4 v[8:11], v87, s[8:9]
	global_load_dwordx4 v[12:15], v88, s[8:9]
	global_load_dwordx4 v[16:19], v89, s[8:9]
	global_load_dwordx4 v[20:23], v90, s[92:93]
	global_load_dwordx4 v[24:27], v90, s[92:93] offset:16
	global_load_dwordx4 v[28:31], v90, s[92:93] offset:32
	global_load_dwordx4 v[32:35], v90, s[92:93] offset:48
	global_load_dwordx4 v[36:39], v91, s[92:93]
	global_load_dwordx4 v[40:43], v91, s[92:93] offset:16
	global_load_dwordx4 v[44:47], v91, s[92:93] offset:32
	global_load_dwordx4 v[48:51], v91, s[92:93] offset:48
	global_load_dwordx4 v[52:55], v92, s[92:93]
	global_load_dwordx4 v[56:59], v92, s[92:93] offset:16
	global_load_dwordx4 v[60:63], v92, s[92:93] offset:32
	global_load_dwordx4 v[64:67], v92, s[92:93] offset:48
	global_load_dwordx4 v[68:71], v93, s[92:93]
	global_load_dwordx4 v[72:75], v93, s[92:93] offset:16
	global_load_dwordx4 v[76:79], v93, s[92:93] offset:32
	global_load_dwordx4 v[80:83], v93, s[92:93] offset:48
	s_waitcnt vmcnt(12)
	v_lshlrev_b32_e32 v104, 16, v4
	v_and_b32_e32 v105, 0xffff0000, v4
	v_lshlrev_b32_e32 v106, 16, v5
	v_and_b32_e32 v107, 0xffff0000, v5
	v_lshlrev_b32_e32 v108, 16, v6
	v_and_b32_e32 v109, 0xffff0000, v6
	v_lshlrev_b32_e32 v110, 16, v7
	v_and_b32_e32 v111, 0xffff0000, v7
	v_xor_b32_e32 v112, v94, v21
	v_xor_b32_e32 v113, v94, v23
	v_xor_b32_e32 v114, v94, v25
	v_xor_b32_e32 v115, v94, v27
	v_xor_b32_e32 v116, v94, v29
	v_xor_b32_e32 v117, v94, v31
	v_xor_b32_e32 v118, v94, v33
	v_xor_b32_e32 v119, v94, v35
	v_mul_f32_dpp v120, v104, v112 quad_perm:[1,0,3,2] row_mask:0xf bank_mask:0xf
	v_mul_f32_dpp v121, v105, v113 quad_perm:[1,0,3,2] row_mask:0xf bank_mask:0xf
	v_mul_f32_dpp v122, v106, v114 quad_perm:[1,0,3,2] row_mask:0xf bank_mask:0xf
	v_mul_f32_dpp v123, v107, v115 quad_perm:[1,0,3,2] row_mask:0xf bank_mask:0xf
	v_mul_f32_dpp v124, v108, v116 quad_perm:[1,0,3,2] row_mask:0xf bank_mask:0xf
	v_mul_f32_dpp v125, v109, v117 quad_perm:[1,0,3,2] row_mask:0xf bank_mask:0xf
	v_mul_f32_dpp v126, v110, v118 quad_perm:[1,0,3,2] row_mask:0xf bank_mask:0xf
	v_mul_f32_dpp v127, v111, v119 quad_perm:[1,0,3,2] row_mask:0xf bank_mask:0xf
	v_fma_f32 v104, v104, v20, v120
	v_fma_f32 v105, v105, v22, v121
	v_fma_f32 v106, v106, v24, v122
	v_fma_f32 v107, v107, v26, v123
	v_fma_f32 v108, v108, v28, v124
	v_fma_f32 v109, v109, v30, v125
	v_fma_f32 v110, v110, v32, v126
	v_fma_f32 v111, v111, v34, v127
	v_cvt_pk_bf16_f32 v4, v104, v105
	v_cvt_pk_bf16_f32 v5, v106, v107
	v_cvt_pk_bf16_f32 v6, v108, v109
	v_cvt_pk_bf16_f32 v7, v110, v111
	global_store_dwordx4 v86, v[4:7], s[8:9]
	s_waitcnt vmcnt(8)
; __device__ __forceinline__ unsigned pk2(float lo, float hi) { return f2bf(lo) | (f2bf(hi) << 16); }
; template <int CTRL> __device__ __forceinline__ float dppf(float v) { return __builtin_bit_cast(float, __builtin_amdgcn_update_dpp(0, __builtin_bit_cast(int, v), CTRL, 0xf, 0xf, false)); }
; __device__ __forceinline__ v4u prep_compute(const v4u rw, const f32x4 (&tb)[4], int type, int sub, const float* qkg) {
;     ...
;     const bool active = isA || sub < 2;
;     const float sg = (isA ? (sub & 2) : (sub & 1)) ? 1.f : -1.f;
; #pragma unroll
;     for (int i = 0; i < 8; ++i) {
;         const float p1 = dppf<DPP_XOR1>(v[i]), p2 = dppf<DPP_XOR2>(v[i]);
;         const float pr = isA ? p2 : p1;
;         const float rv = v[i] * cc[i] + sg * (pr * sn[i]);
;         v[i] = active ? rv : v[i];
;     }
;     v4u o; o.x = pk2(v[0], v[1]); o.y = pk2(v[2], v[3]); o.z = pk2(v[4], v[5]); o.w = pk2(v[6], v[7]);
;     __device__ __forceinline__ void done(const pg8::Unit& u) const {
;     ...
; #pragma unroll 1
;         for (int it = 0; it < nit; it += U) {
;             bf16* p[U]; int type[U]; v4u raw[U]; f32x4 tb[U][4];
; #pragma unroll
;             for (int k = 0; k < U; ++k) {
;                 const int hvi = (it + k) * 64 + gidx, rl = (nh == 2) ? (hvi >> 1) : (hvi >> 2), col = colt + 64 * ((nh == 2) ? (hvi & 1) : (hvi & 3)), row = u.pm * 256 + rl;
;                 const int ty = (even && colt == 512) ? 1 : 3;
;                 type[k] = ty; p[k] = QKV + (size_t)row * PITCH + col + 8 * sub;
;                 raw[k] = *(const v4u*)p[k];
;                 const int t = row < MP ? (row & 8191) : (row & 4095);
;                 const int aidx = (sub < 4) ? (t >> 6) : (t & 63);
;                 const f32x2* cs = (ty < 2) ? axT + aidx * 16 + 8 * (sub & 1) : ropeT + t * 8;
;                 tb[k][0] = *(const f32x4*)(cs); tb[k][1] = *(const f32x4*)(cs + 2); tb[k][2] = *(const f32x4*)(cs + 4); tb[k][3] = *(const f32x4*)(cs + 6);
;             }
; #pragma unroll
;             for (int k = 0; k < U; ++k) *(v4u*)p[k] = prep_compute(raw[k], tb[k], type[k], sub, qkg);
	v_lshlrev_b32_e32 v104, 16, v8
	v_and_b32_e32 v105, 0xffff0000, v8
	v_lshlrev_b32_e32 v106, 16, v9
	v_and_b32_e32 v107, 0xffff0000, v9
	v_lshlrev_b32_e32 v108, 16, v10
	v_and_b32_e32 v109, 0xffff0000, v10
	v_lshlrev_b32_e32 v110, 16, v11
	v_and_b32_e32 v111, 0xffff0000, v11
	v_xor_b32_e32 v112, v94, v37
	v_xor_b32_e32 v113, v94, v39
	v_xor_b32_e32 v114, v94, v41
	v_xor_b32_e32 v115, v94, v43
	v_xor_b32_e32 v116, v94, v45
	v_xor_b32_e32 v117, v94, v47
	v_xor_b32_e32 v118, v94, v49
	v_xor_b32_e32 v119, v94, v51
	v_mul_f32_dpp v120, v104, v112 quad_perm:[1,0,3,2] row_mask:0xf bank_mask:0xf
	v_mul_f32_dpp v121, v105, v113 quad_perm:[1,0,3,2] row_mask:0xf bank_mask:0xf
	v_mul_f32_dpp v122, v106, v114 quad_perm:[1,0,3,2] row_mask:0xf bank_mask:0xf
	v_mul_f32_dpp v123, v107, v115 quad_perm:[1,0,3,2] row_mask:0xf bank_mask:0xf
	v_mul_f32_dpp v124, v108, v116 quad_perm:[1,0,3,2] row_mask:0xf bank_mask:0xf
	v_mul_f32_dpp v125, v109, v117 quad_perm:[1,0,3,2] row_mask:0xf bank_mask:0xf
	v_mul_f32_dpp v126, v110, v118 quad_perm:[1,0,3,2] row_mask:0xf bank_mask:0xf
	v_mul_f32_dpp v127, v111, v119 quad_perm:[1,0,3,2] row_mask:0xf bank_mask:0xf
	v_fma_f32 v104, v104, v36, v120
	v_fma_f32 v105, v105, v38, v121
	v_fma_f32 v106, v106, v40, v122
	v_fma_f32 v107, v107, v42, v123
	v_fma_f32 v108, v108, v44, v124
	v_fma_f32 v109, v109, v46, v125
	v_fma_f32 v110, v110, v48, v126
	v_fma_f32 v111, v111, v50, v127
	v_cvt_pk_bf16_f32 v8, v104, v105
	v_cvt_pk_bf16_f32 v9, v106, v107
	v_cvt_pk_bf16_f32 v10, v108, v109
	v_cvt_pk_bf16_f32 v11, v110, v111
	global_store_dwordx4 v87, v[8:11], s[8:9]
	s_waitcnt vmcnt(4)
	v_lshlrev_b32_e32 v104, 16, v12
	v_and_b32_e32 v105, 0xffff0000, v12
	v_lshlrev_b32_e32 v106, 16, v13
	v_and_b32_e32 v107, 0xffff0000, v13
	v_lshlrev_b32_e32 v108, 16, v14
	v_and_b32_e32 v109, 0xffff0000, v14
	v_lshlrev_b32_e32 v110, 16, v15
	v_and_b32_e32 v111, 0xffff0000, v15
	v_xor_b32_e32 v112, v94, v53
	v_xor_b32_e32 v113, v94, v55
	v_xor_b32_e32 v114, v94, v57
	v_xor_b32_e32 v115, v94, v59
	v_xor_b32_e32 v116, v94, v61
	v_xor_b32_e32 v117, v94, v63
	v_xor_b32_e32 v118, v94, v65
	v_xor_b32_e32 v119, v94, v67
	v_mul_f32_dpp v120, v104, v112 quad_perm:[1,0,3,2] row_mask:0xf bank_mask:0xf
	v_mul_f32_dpp v121, v105, v113 quad_perm:[1,0,3,2] row_mask:0xf bank_mask:0xf
	v_mul_f32_dpp v122, v106, v114 quad_perm:[1,0,3,2] row_mask:0xf bank_mask:0xf
	v_mul_f32_dpp v123, v107, v115 quad_perm:[1,0,3,2] row_mask:0xf bank_mask:0xf
	v_mul_f32_dpp v124, v108, v116 quad_perm:[1,0,3,2] row_mask:0xf bank_mask:0xf
	v_mul_f32_dpp v125, v109, v117 quad_perm:[1,0,3,2] row_mask:0xf bank_mask:0xf
	v_mul_f32_dpp v126, v110, v118 quad_perm:[1,0,3,2] row_mask:0xf bank_mask:0xf
	v_mul_f32_dpp v127, v111, v119 quad_perm:[1,0,3,2] row_mask:0xf bank_mask:0xf
	v_fma_f32 v104, v104, v52, v120
	v_fma_f32 v105, v105, v54, v121
	v_fma_f32 v106, v106, v56, v122
	v_fma_f32 v107, v107, v58, v123
	v_fma_f32 v108, v108, v60, v124
	v_fma_f32 v109, v109, v62, v125
	v_fma_f32 v110, v110, v64, v126
	v_fma_f32 v111, v111, v66, v127
	v_cvt_pk_bf16_f32 v12, v104, v105
	v_cvt_pk_bf16_f32 v13, v106, v107
	v_cvt_pk_bf16_f32 v14, v108, v109
	v_cvt_pk_bf16_f32 v15, v110, v111
	global_store_dwordx4 v88, v[12:15], s[8:9]
	s_waitcnt vmcnt(0)
	v_lshlrev_b32_e32 v104, 16, v16
	v_and_b32_e32 v105, 0xffff0000, v16
	v_lshlrev_b32_e32 v106, 16, v17
	v_and_b32_e32 v107, 0xffff0000, v17
	v_lshlrev_b32_e32 v108, 16, v18
	v_and_b32_e32 v109, 0xffff0000, v18
	v_lshlrev_b32_e32 v110, 16, v19
	v_and_b32_e32 v111, 0xffff0000, v19
	v_xor_b32_e32 v112, v94, v69
	v_xor_b32_e32 v113, v94, v71
	v_xor_b32_e32 v114, v94, v73
	v_xor_b32_e32 v115, v94, v75
	v_xor_b32_e32 v116, v94, v77
	v_xor_b32_e32 v117, v94, v79
	v_xor_b32_e32 v118, v94, v81
	v_xor_b32_e32 v119, v94, v83
	v_mul_f32_dpp v120, v104, v112 quad_perm:[1,0,3,2] row_mask:0xf bank_mask:0xf
	v_mul_f32_dpp v121, v105, v113 quad_perm:[1,0,3,2] row_mask:0xf bank_mask:0xf
	v_mul_f32_dpp v122, v106, v114 quad_perm:[1,0,3,2] row_mask:0xf bank_mask:0xf
	v_mul_f32_dpp v123, v107, v115 quad_perm:[1,0,3,2] row_mask:0xf bank_mask:0xf
	v_mul_f32_dpp v124, v108, v116 quad_perm:[1,0,3,2] row_mask:0xf bank_mask:0xf
	v_mul_f32_dpp v125, v109, v117 quad_perm:[1,0,3,2] row_mask:0xf bank_mask:0xf
	v_mul_f32_dpp v126, v110, v118 quad_perm:[1,0,3,2] row_mask:0xf bank_mask:0xf
	v_mul_f32_dpp v127, v111, v119 quad_perm:[1,0,3,2] row_mask:0xf bank_mask:0xf
	v_fma_f32 v104, v104, v68, v120
	v_fma_f32 v105, v105, v70, v121
	v_fma_f32 v106, v106, v72, v122
	v_fma_f32 v107, v107, v74, v123
	v_fma_f32 v108, v108, v76, v124
	v_fma_f32 v109, v109, v78, v125
	v_fma_f32 v110, v110, v80, v126
	v_fma_f32 v111, v111, v82, v127
	v_cvt_pk_bf16_f32 v16, v104, v105
	v_cvt_pk_bf16_f32 v17, v106, v107
	v_cvt_pk_bf16_f32 v18, v108, v109
	v_cvt_pk_bf16_f32 v19, v110, v111
	global_store_dwordx4 v89, v[16:19], s[8:9]
	s_branch .LBB0_220
